# grid barrier: waiting workgroups poll the top-level generation word directly (released when the last XCD leader arrives; no per-XCD generation hop)
# baseline (speedup 1.0000x reference)
.LBB0_73:
	s_lshl_b32 s24, s39, 6
	s_add_i32 s4, s24, 0x500
	s_mov_b32 s5, 0
	s_lshl_b64 s[0:1], s[4:5], 2
	s_add_u32 s0, s6, s0
	s_addc_u32 s1, s7, s1
	v_mov_b32_e32 v1, 1
	v_mov_b64_e32 v[4:5], s[0:1]
	flat_atomic_add v1, v[4:5], v1 sc0
	v_cvt_f32_u32_e32 v3, v2
	v_sub_u32_e32 v4, 0, v2
	v_rcp_iflag_f32_e32 v3, v3
	s_nop 0
	v_mul_f32_e32 v3, 0x4f7ffffe, v3
	v_cvt_u32_f32_e32 v3, v3
	v_mul_lo_u32 v4, v4, v3
	v_mul_hi_u32 v4, v3, v4
	v_add_u32_e32 v3, v3, v4
	s_waitcnt vmcnt(0) lgkmcnt(0)
	v_mul_hi_u32 v3, v1, v3
	v_mul_lo_u32 v5, v3, v2
	v_add_u32_e32 v4, 1, v1
	v_sub_u32_e32 v1, v1, v5
	v_add_u32_e32 v6, 1, v3
	v_cmp_ge_u32_e32 vcc, v1, v2
	v_sub_u32_e32 v5, v1, v2
	s_nop 0
	v_cndmask_b32_e32 v3, v3, v6, vcc
	v_cndmask_b32_e32 v1, v1, v5, vcc
	v_add_u32_e32 v5, 1, v3
	v_cmp_ge_u32_e32 vcc, v1, v2
	s_nop 1
	v_cndmask_b32_e32 v1, v3, v5, vcc
	v_mad_u64_u32 v[2:3], s[0:1], v2, v1, v[2:3]
	v_cmp_ne_u32_e32 vcc, v4, v2
	s_and_saveexec_b64 s[0:1], vcc
	s_xor_b64 s[0:1], exec, s[0:1]
	s_cbranch_execz .LBB0_86
	s_add_i32 s4, s24, 0x900
	s_lshl_b64 s[4:5], s[4:5], 2
	s_add_u32 s8, s6, 0x3500
	s_addc_u32 s9, s7, 0
	v_mov_b64_e32 v[2:3], s[8:9]
	flat_load_dword v0, v[2:3] sc1
	s_waitcnt vmcnt(0) lgkmcnt(0)
	v_cmp_eq_u32_e32 vcc, v0, v1
	s_and_saveexec_b64 s[4:5], vcc
	s_cbranch_execz .LBB0_85
	s_mov_b32 s25, 1
	s_mov_b64 s[10:11], 0
	s_branch .LBB0_77

.LBB0_126:
	s_lshl_b32 s24, s39, 6
	s_add_i32 s4, s24, 0x500
	s_mov_b32 s5, 0
	s_lshl_b64 s[0:1], s[4:5], 2
	s_add_u32 s0, s36, s0
	s_addc_u32 s1, s37, s1
	v_mov_b32_e32 v1, 1
	v_mov_b64_e32 v[4:5], s[0:1]
	flat_atomic_add v1, v[4:5], v1 sc0
	v_cvt_f32_u32_e32 v3, v2
	v_sub_u32_e32 v4, 0, v2
	v_rcp_iflag_f32_e32 v3, v3
	s_nop 0
	v_mul_f32_e32 v3, 0x4f7ffffe, v3
	v_cvt_u32_f32_e32 v3, v3
	v_mul_lo_u32 v4, v4, v3
	v_mul_hi_u32 v4, v3, v4
	v_add_u32_e32 v3, v3, v4
	s_waitcnt vmcnt(0) lgkmcnt(0)
	v_mul_hi_u32 v3, v1, v3
	v_mul_lo_u32 v5, v3, v2
	v_add_u32_e32 v4, 1, v1
	v_sub_u32_e32 v1, v1, v5
	v_add_u32_e32 v6, 1, v3
	v_cmp_ge_u32_e32 vcc, v1, v2
	v_sub_u32_e32 v5, v1, v2
	s_nop 0
	v_cndmask_b32_e32 v3, v3, v6, vcc
	v_cndmask_b32_e32 v1, v1, v5, vcc
	v_add_u32_e32 v5, 1, v3
	v_cmp_ge_u32_e32 vcc, v1, v2
	s_nop 1
	v_cndmask_b32_e32 v1, v3, v5, vcc
	v_mad_u64_u32 v[2:3], s[0:1], v2, v1, v[2:3]
	v_cmp_ne_u32_e32 vcc, v4, v2
	s_and_saveexec_b64 s[0:1], vcc
	s_xor_b64 s[0:1], exec, s[0:1]
	s_cbranch_execz .LBB0_139
	s_add_i32 s4, s24, 0x900
	s_lshl_b64 s[4:5], s[4:5], 2
	s_add_u32 s8, s36, 0x3500
	s_addc_u32 s9, s37, 0
	v_mov_b64_e32 v[2:3], s[8:9]
	flat_load_dword v0, v[2:3] sc1
	s_waitcnt vmcnt(0) lgkmcnt(0)
	v_cmp_eq_u32_e32 vcc, v0, v1
	s_and_saveexec_b64 s[4:5], vcc
	s_cbranch_execz .LBB0_138
	s_mov_b32 s25, 1
	s_mov_b64 s[10:11], 0
	s_branch .LBB0_130

.LBB0_371:
	s_lshl_b32 s6, s6, 6
	s_add_i32 s68, s6, 0x500
	s_lshl_b64 s[0:1], s[68:69], 2
	s_add_u32 s0, s52, s0
	s_addc_u32 s1, s53, s1
	v_mov_b64_e32 v[4:5], s[0:1]
	flat_atomic_add v4, v[4:5], v213 sc0
	v_cvt_f32_u32_e32 v3, v2
	v_sub_u32_e32 v5, 0, v2
	v_rcp_iflag_f32_e32 v3, v3
	s_nop 0
	v_mul_f32_e32 v3, 0x4f7ffffe, v3
	v_cvt_u32_f32_e32 v3, v3
	v_mul_lo_u32 v5, v5, v3
	v_mul_hi_u32 v5, v3, v5
	v_add_u32_e32 v3, v3, v5
	s_waitcnt vmcnt(0) lgkmcnt(0)
	v_mul_hi_u32 v3, v4, v3
	v_mul_lo_u32 v5, v3, v2
	v_sub_u32_e32 v5, v4, v5
	v_cmp_ge_u32_e32 vcc, v5, v2
	v_add_u32_e32 v6, 1, v3
	s_nop 0
	v_cndmask_b32_e32 v3, v3, v6, vcc
	v_sub_u32_e32 v6, v5, v2
	v_cndmask_b32_e32 v5, v5, v6, vcc
	v_cmp_ge_u32_e32 vcc, v5, v2
	v_add_u32_e32 v5, 1, v3
	v_add_u32_e32 v6, 1, v4
	v_cndmask_b32_e32 v3, v3, v5, vcc
	v_mad_u64_u32 v[4:5], s[0:1], v2, v3, v[2:3]
	v_cmp_ne_u32_e32 vcc, v6, v4
	s_and_saveexec_b64 s[0:1], vcc
	s_xor_b64 s[0:1], exec, s[0:1]
	s_cbranch_execz .LBB0_384
	s_add_i32 s68, s6, 0x900
	s_lshl_b64 s[2:3], s[68:69], 2
	s_add_u32 s4, s52, 0x3500
	s_addc_u32 s5, s53, 0
	v_mov_b64_e32 v[4:5], s[4:5]
	flat_load_dword v0, v[4:5] sc1
	s_waitcnt vmcnt(0) lgkmcnt(0)
	v_cmp_eq_u32_e32 vcc, v0, v3
	s_and_saveexec_b64 s[2:3], vcc
	s_cbranch_execz .LBB0_383
	s_mov_b32 s7, 1
	s_mov_b64 s[8:9], 0
	s_branch .LBB0_375

.LBB0_610:
	s_lshl_b32 s6, s6, 6
	s_add_i32 s68, s6, 0x500
	s_lshl_b64 s[0:1], s[68:69], 2
	s_add_u32 s0, s38, s0
	s_addc_u32 s1, s39, s1
	v_mov_b64_e32 v[4:5], s[0:1]
	flat_atomic_add v4, v[4:5], v213 sc0
	v_cvt_f32_u32_e32 v3, v2
	v_sub_u32_e32 v5, 0, v2
	v_rcp_iflag_f32_e32 v3, v3
	s_nop 0
	v_mul_f32_e32 v3, 0x4f7ffffe, v3
	v_cvt_u32_f32_e32 v3, v3
	v_mul_lo_u32 v5, v5, v3
	v_mul_hi_u32 v5, v3, v5
	v_add_u32_e32 v3, v3, v5
	s_waitcnt vmcnt(0) lgkmcnt(0)
	v_mul_hi_u32 v3, v4, v3
	v_mul_lo_u32 v5, v3, v2
	v_sub_u32_e32 v5, v4, v5
	v_cmp_ge_u32_e32 vcc, v5, v2
	v_add_u32_e32 v6, 1, v3
	s_nop 0
	v_cndmask_b32_e32 v3, v3, v6, vcc
	v_sub_u32_e32 v6, v5, v2
	v_cndmask_b32_e32 v5, v5, v6, vcc
	v_cmp_ge_u32_e32 vcc, v5, v2
	v_add_u32_e32 v5, 1, v3
	v_add_u32_e32 v6, 1, v4
	v_cndmask_b32_e32 v3, v3, v5, vcc
	v_mad_u64_u32 v[4:5], s[0:1], v2, v3, v[2:3]
	v_cmp_ne_u32_e32 vcc, v6, v4
	s_and_saveexec_b64 s[0:1], vcc
	s_xor_b64 s[0:1], exec, s[0:1]
	s_cbranch_execz .LBB0_623
	s_add_i32 s68, s6, 0x900
	s_lshl_b64 s[2:3], s[68:69], 2
	s_add_u32 s4, s38, 0x3500
	s_addc_u32 s5, s39, 0
	v_mov_b64_e32 v[4:5], s[4:5]
	flat_load_dword v0, v[4:5] sc1
	s_waitcnt vmcnt(0) lgkmcnt(0)
	v_cmp_eq_u32_e32 vcc, v0, v3
	s_and_saveexec_b64 s[2:3], vcc
	s_cbranch_execz .LBB0_622
	s_mov_b32 s7, 1
	s_mov_b64 s[8:9], 0
	s_branch .LBB0_614

.LBB0_688:
	s_lshl_b32 s6, s6, 6
	s_add_i32 s68, s6, 0x500
	s_lshl_b64 s[0:1], s[68:69], 2
	s_add_u32 s0, s46, s0
	s_addc_u32 s1, s47, s1
	v_mov_b64_e32 v[4:5], s[0:1]
	flat_atomic_add v4, v[4:5], v213 sc0
	v_cvt_f32_u32_e32 v3, v2
	v_sub_u32_e32 v5, 0, v2
	v_rcp_iflag_f32_e32 v3, v3
	s_nop 0
	v_mul_f32_e32 v3, 0x4f7ffffe, v3
	v_cvt_u32_f32_e32 v3, v3
	v_mul_lo_u32 v5, v5, v3
	v_mul_hi_u32 v5, v3, v5
	v_add_u32_e32 v3, v3, v5
	s_waitcnt vmcnt(0) lgkmcnt(0)
	v_mul_hi_u32 v3, v4, v3
	v_mul_lo_u32 v5, v3, v2
	v_sub_u32_e32 v5, v4, v5
	v_cmp_ge_u32_e32 vcc, v5, v2
	v_add_u32_e32 v6, 1, v3
	s_nop 0
	v_cndmask_b32_e32 v3, v3, v6, vcc
	v_sub_u32_e32 v6, v5, v2
	v_cndmask_b32_e32 v5, v5, v6, vcc
	v_cmp_ge_u32_e32 vcc, v5, v2
	v_add_u32_e32 v5, 1, v3
	v_add_u32_e32 v6, 1, v4
	v_cndmask_b32_e32 v3, v3, v5, vcc
	v_mad_u64_u32 v[4:5], s[0:1], v2, v3, v[2:3]
	v_cmp_ne_u32_e32 vcc, v6, v4
	s_and_saveexec_b64 s[0:1], vcc
	s_xor_b64 s[0:1], exec, s[0:1]
	s_cbranch_execz .LBB0_701
	s_add_i32 s68, s6, 0x900
	s_lshl_b64 s[2:3], s[68:69], 2
	s_add_u32 s4, s46, 0x3500
	s_addc_u32 s5, s47, 0
	v_mov_b64_e32 v[4:5], s[4:5]
	flat_load_dword v0, v[4:5] sc1
	s_waitcnt vmcnt(0) lgkmcnt(0)
	v_cmp_eq_u32_e32 vcc, v0, v3
	s_and_saveexec_b64 s[2:3], vcc
	s_cbranch_execz .LBB0_700
	s_mov_b32 s7, 1
	s_mov_b64 s[8:9], 0
	s_branch .LBB0_692

.LBB0_745:
	s_lshl_b32 s6, s6, 6
	s_add_i32 s68, s6, 0x500
	s_lshl_b64 s[0:1], s[68:69], 2
	s_add_u32 s0, s4, s0
	s_addc_u32 s1, s5, s1
	v_mov_b64_e32 v[4:5], s[0:1]
	flat_atomic_add v4, v[4:5], v213 sc0
	v_cvt_f32_u32_e32 v3, v2
	v_sub_u32_e32 v5, 0, v2
	v_rcp_iflag_f32_e32 v3, v3
	s_nop 0
	v_mul_f32_e32 v3, 0x4f7ffffe, v3
	v_cvt_u32_f32_e32 v3, v3
	v_mul_lo_u32 v5, v5, v3
	v_mul_hi_u32 v5, v3, v5
	v_add_u32_e32 v3, v3, v5
	s_waitcnt vmcnt(0) lgkmcnt(0)
	v_mul_hi_u32 v3, v4, v3
	v_mul_lo_u32 v5, v3, v2
	v_sub_u32_e32 v5, v4, v5
	v_cmp_ge_u32_e32 vcc, v5, v2
	v_add_u32_e32 v6, 1, v3
	s_nop 0
	v_cndmask_b32_e32 v3, v3, v6, vcc
	v_sub_u32_e32 v6, v5, v2
	v_cndmask_b32_e32 v5, v5, v6, vcc
	v_cmp_ge_u32_e32 vcc, v5, v2
	v_add_u32_e32 v5, 1, v3
	v_add_u32_e32 v6, 1, v4
	v_cndmask_b32_e32 v3, v3, v5, vcc
	v_mad_u64_u32 v[4:5], s[0:1], v2, v3, v[2:3]
	v_cmp_ne_u32_e32 vcc, v6, v4
	s_and_saveexec_b64 s[0:1], vcc
	s_xor_b64 s[0:1], exec, s[0:1]
	s_cbranch_execz .LBB0_758
	s_add_i32 s68, s6, 0x900
	s_lshl_b64 s[2:3], s[68:69], 2
	s_add_u32 s8, s4, 0x3500
	s_addc_u32 s9, s5, 0
	v_mov_b64_e32 v[4:5], s[8:9]
	flat_load_dword v0, v[4:5] sc1
	s_waitcnt vmcnt(0) lgkmcnt(0)
	v_cmp_eq_u32_e32 vcc, v0, v3
	s_and_saveexec_b64 s[2:3], vcc
	s_cbranch_execz .LBB0_757
	s_mov_b32 s7, 1
	s_mov_b64 s[10:11], 0
	s_branch .LBB0_749
